# attention interior loop: QK as two accumulate chains (keys 0-31 then 32-63), V reads at the top, first-half softmax in the shadow of the second chain
# baseline (speedup 1.0000x reference)
.Lattn_rot:
	s_waitcnt lgkmcnt(0)
	v_lshl_add_u32 v108, s43, 13, v131
	ds_read_b64_tr_b16 v[132:133], v108 offset:0
	ds_read_b64_tr_b16 v[134:135], v108 offset:1024
	ds_read_b64_tr_b16 v[160:161], v108 offset:64
	ds_read_b64_tr_b16 v[162:163], v108 offset:1088
	ds_read_b64_tr_b16 v[126:127], v108 offset:2048
	ds_read_b64_tr_b16 v[128:129], v108 offset:3072
	ds_read_b64_tr_b16 v[122:123], v108 offset:2112
	ds_read_b64_tr_b16 v[124:125], v108 offset:3136
	ds_read_b64_tr_b16 v[118:119], v108 offset:4096
	ds_read_b64_tr_b16 v[120:121], v108 offset:5120
	ds_read_b64_tr_b16 v[114:115], v108 offset:4160
	ds_read_b64_tr_b16 v[116:117], v108 offset:5184
	ds_read_b64_tr_b16 v[110:111], v108 offset:6144
	ds_read_b64_tr_b16 v[112:113], v108 offset:7168
	ds_read_b64_tr_b16 v[106:107], v108 offset:6208
	ds_read_b64_tr_b16 v[108:109], v108 offset:7232
	v_mfma_f32_32x32x16_bf16 v[48:63], v[204:207], v[82:85], 0
	s_add_i32 s4, s49, 2
	s_cmp_lt_u32 s4, s36
	s_cselect_b32 s4, s4, s48
	s_mul_i32 s14, s4, 0x3000
	s_mul_hi_u32 s15, s4, 0x3000
	s_add_u32 s14, s6, s14
	s_mul_i32 s52, s37, 0x3000
	s_addc_u32 s15, s7, s15
	s_add_i32 s52, s33, s52
	v_lshl_add_u64 v[172:173], v[144:145], 1, s[14:15]
	s_mov_b32 m0, s52
	s_andn2_b64 vcc, exec, s[10:11]
	global_load_lds_dwordx4 v[172:173], off
	v_mfma_f32_32x32x16_bf16 v[48:63], v[208:211], v[86:89], v[48:63]
	v_mfma_f32_32x32x16_bf16 v[48:63], v[220:223], v[90:93], v[48:63]
	s_cbranch_vccnz .LBB0_106
	v_lshl_add_u64 v[172:173], v[80:81], 1, s[14:15]
	s_add_i32 m0, s52, 0x2000
	s_nop 0
	global_load_lds_dwordx4 v[172:173], off
.LBB0_106:
	v_mfma_f32_32x32x16_bf16 v[48:63], v[224:227], v[94:97], v[48:63]
	v_mfma_f32_32x32x16_bf16 v[48:63], v[176:179], v[98:101], v[48:63]
	s_lshl_b64 s[14:15], s[4:5], 17
	s_lshl_b32 s4, s37, 13
	v_lshl_add_u64 v[172:173], v[146:147], 0, s[14:15]
	s_add_i32 s4, s33, s4
	v_lshl_add_u64 v[172:173], v[172:173], 0, s[20:21]
	s_add_i32 m0, s4, 0x9000
	global_load_lds_dwordx4 v[172:173], off
	v_mfma_f32_32x32x16_bf16 v[48:63], v[184:187], v[102:105], v[48:63]
	v_mfma_f32_32x32x16_bf16 v[64:79], v[212:215], v[82:85], 0
	v_mfma_f32_32x32x16_bf16 v[64:79], v[216:219], v[86:89], v[64:79]
	s_mul_i32 s14, s45, 0x3000
	s_add_i32 s14, s14, 16
	v_add_u32_e32 v174, s14, v149
	v_mfma_f32_32x32x16_bf16 v[64:79], v[228:231], v[90:93], v[64:79]
	s_nop 5
	v_exp_f32_e32 v50, v50
	v_exp_f32_e32 v51, v51
	v_exp_f32_e32 v52, v52
	v_exp_f32_e32 v53, v53
	v_exp_f32_e32 v54, v54
	v_exp_f32_e32 v55, v55
	v_exp_f32_e32 v48, v48
	v_exp_f32_e32 v49, v49
	v_mfma_f32_32x32x16_bf16 v[64:79], v[232:235], v[94:97], v[64:79]
	v_add_f32_e32 v32, v32, v50
	v_add_f32_e32 v33, v33, v51
	v_add_f32_e32 v34, v34, v52
	v_add_f32_e32 v35, v35, v53
	v_add_f32_e32 v32, v32, v54
	v_add_f32_e32 v33, v33, v55
	v_add_f32_e32 v34, v34, v48
	v_add_f32_e32 v35, v35, v49
	v_mfma_f32_32x32x16_bf16 v[64:79], v[180:183], v[98:101], v[64:79]
	s_waitcnt lgkmcnt(0)
	v_cvt_pk_bf16_f32 v48, v48, v49
	v_cvt_pk_bf16_f32 v49, v50, v51
	v_cvt_pk_bf16_f32 v50, v52, v53
	v_cvt_pk_bf16_f32 v51, v54, v55
	v_exp_f32_e32 v56, v56
	v_exp_f32_e32 v57, v57
	v_exp_f32_e32 v58, v58
	v_exp_f32_e32 v59, v59
	v_mfma_f32_32x32x16_bf16 v[64:79], v[188:191], v[102:105], v[64:79]
	v_exp_f32_e32 v60, v60
	v_exp_f32_e32 v61, v61
	v_exp_f32_e32 v62, v62
	v_exp_f32_e32 v63, v63
	v_mfma_f32_32x32x16_bf16 v[0:15], v[132:135], v[48:51], v[0:15]
	v_add_f32_e32 v32, v32, v56
	v_add_f32_e32 v33, v33, v57
	v_add_f32_e32 v34, v34, v58
	v_add_f32_e32 v35, v35, v59
	v_add_f32_e32 v32, v32, v60
	v_add_f32_e32 v33, v33, v61
	v_add_f32_e32 v34, v34, v62
	v_add_f32_e32 v35, v35, v63
	v_mfma_f32_32x32x16_bf16 v[16:31], v[160:163], v[48:51], v[16:31]
	v_cvt_pk_bf16_f32 v52, v56, v57
	v_cvt_pk_bf16_f32 v53, v58, v59
	v_cvt_pk_bf16_f32 v54, v60, v61
	v_cvt_pk_bf16_f32 v55, v62, v63
	ds_read_b128 v[204:207], v174
	ds_read_b128 v[208:211], v174 offset:32
	ds_read_b128 v[212:215], v174 offset:6144
	v_mfma_f32_32x32x16_bf16 v[0:15], v[126:129], v[52:55], v[0:15]
	v_mfma_f32_32x32x16_bf16 v[16:31], v[122:125], v[52:55], v[16:31]
	v_exp_f32_e32 v64, v64
	v_exp_f32_e32 v65, v65
	v_exp_f32_e32 v66, v66
	v_exp_f32_e32 v67, v67
	v_exp_f32_e32 v68, v68
	v_exp_f32_e32 v69, v69
	v_exp_f32_e32 v70, v70
	v_exp_f32_e32 v71, v71
	v_add_f32_e32 v32, v32, v64
	v_add_f32_e32 v33, v33, v65
	v_add_f32_e32 v34, v34, v66
	v_add_f32_e32 v35, v35, v67
	v_add_f32_e32 v32, v32, v68
	v_add_f32_e32 v33, v33, v69
	v_add_f32_e32 v34, v34, v70
	v_add_f32_e32 v35, v35, v71
	v_cvt_pk_bf16_f32 v48, v64, v65
	v_cvt_pk_bf16_f32 v49, v66, v67
	v_cvt_pk_bf16_f32 v50, v68, v69
	v_cvt_pk_bf16_f32 v51, v70, v71
	ds_read_b128 v[216:219], v174 offset:6176
	ds_read_b128 v[220:223], v174 offset:64
	ds_read_b128 v[224:227], v174 offset:96
	v_mfma_f32_32x32x16_bf16 v[0:15], v[118:121], v[48:51], v[0:15]
	v_mfma_f32_32x32x16_bf16 v[16:31], v[114:117], v[48:51], v[16:31]
	v_exp_f32_e32 v72, v72
	v_exp_f32_e32 v73, v73
	v_exp_f32_e32 v74, v74
	v_exp_f32_e32 v75, v75
	v_exp_f32_e32 v76, v76
	v_exp_f32_e32 v77, v77
	v_exp_f32_e32 v78, v78
	v_exp_f32_e32 v79, v79
	v_add_f32_e32 v32, v32, v72
	v_add_f32_e32 v33, v33, v73
	v_add_f32_e32 v34, v34, v74
	v_add_f32_e32 v35, v35, v75
	v_add_f32_e32 v32, v32, v76
	v_add_f32_e32 v33, v33, v77
	v_add_f32_e32 v34, v34, v78
	v_add_f32_e32 v35, v35, v79
	v_cvt_pk_bf16_f32 v52, v72, v73
	v_cvt_pk_bf16_f32 v53, v74, v75
	v_cvt_pk_bf16_f32 v54, v76, v77
	v_cvt_pk_bf16_f32 v55, v78, v79
	ds_read_b128 v[228:231], v174 offset:6208
	ds_read_b128 v[232:235], v174 offset:6240
	v_add_u32_e32 v175, s14, v150
	ds_read_b128 v[176:179], v175
	ds_read_b128 v[180:183], v175 offset:6144
	v_add_u32_e32 v174, s14, v151
	ds_read_b128 v[184:187], v174
	ds_read_b128 v[188:191], v174 offset:6144
	v_mfma_f32_32x32x16_bf16 v[0:15], v[110:113], v[52:55], v[0:15]
	v_mfma_f32_32x32x16_bf16 v[16:31], v[106:109], v[52:55], v[16:31]
	s_waitcnt vmcnt(0)
	s_add_i32 s49, s49, 1
	s_cmp_eq_u32 s42, s49
	s_cselect_b32 s13, s13, s45
	s_cselect_b32 s45, s45, s37
	s_cselect_b32 s37, s37, s43
	s_cselect_b32 s43, s43, s13
	s_barrier
	s_cbranch_scc1 .LBB0_113
	s_branch .Lattn_rot
